# first K-loop iteration of every GEMM unit peeled: accumulators start from srcC=0 in the first MFMA of each, the 128 zeroing v_mov per unit removed (on top of the GEMM4 store/final_g changes)
# speedup vs baseline: 1.0253x; 1.0057x over previous
.LBB0_271:
	s_ashr_i32 s63, s62, 31
	s_lshl_b64 s[0:1], s[62:63], 20
	s_add_u32 s66, s49, s0
	s_addc_u32 s67, s82, s1
	s_and_b64 s[0:1], s[4:5], exec
	s_cselect_b32 s0, s67, s75
	s_cselect_b32 s1, s66, s74
	s_ashr_i32 s65, s64, 31
	s_lshl_b64 s[68:69], s[64:65], 20
	s_add_u32 s68, s45, s68
	s_addc_u32 s69, s47, s69
	s_and_b64 s[78:79], s[4:5], exec
	s_cselect_b32 s3, s69, s77
	s_cselect_b32 s63, s68, s76
	s_add_u32 s74, s74, 0x80080
	s_addc_u32 s75, s75, 0
	s_add_u32 s65, s76, 0x100
	s_addc_u32 s71, s77, 0
	s_mov_b32 s90, -2
	s_waitcnt vmcnt(0)
	ds_read_b128 v[146:149], v166
	ds_read_b128 v[150:153], v166 offset:1024
	ds_read_b128 v[154:157], v166 offset:2048
	ds_read_b128 v[170:173], v166 offset:3072
	ds_read_b128 v[174:177], v167
	ds_read_b128 v[178:181], v167 offset:1024
	ds_read_b128 v[182:185], v167 offset:2048
	ds_read_b128 v[186:189], v167 offset:3072
	s_add_u32 s76, s74, 0xfff80080
	s_addc_u32 s77, s75, -1
	s_cmp_eq_u32 s90, 28
	s_cselect_b32 s79, s0, s77
	s_cselect_b32 s78, s1, s76
	s_cselect_b32 s77, s3, s71
	s_cselect_b32 s76, s63, s65
	v_lshl_add_u64 v[158:159], s[74:75], 0, v[138:139]
	s_add_i32 m0, s31, 0xc000
	ds_read_b128 v[190:193], v168
	ds_read_b128 v[194:197], v168 offset:1024
	ds_read_b128 v[198:201], v168 offset:2048
	ds_read_b128 v[202:205], v168 offset:3072
	ds_read_b128 v[206:209], v168 offset:4096
	ds_read_b128 v[214:217], v168 offset:5120
	ds_read_b128 v[218:221], v168 offset:6144
	ds_read_b128 v[222:225], v168 offset:7168
	global_load_lds_dwordx4 v[158:159], off
	v_lshl_add_u64 v[158:159], s[74:75], 0, v[140:141]
	s_add_i32 m0, s31, 0xe000
	s_nop 0
	global_load_lds_dwordx4 v[158:159], off
	s_waitcnt vmcnt(8)
	s_waitcnt lgkmcnt(0)
	s_barrier
	s_setprio 1
	s_waitcnt lgkmcnt(0)
	v_mfma_f32_16x16x32_bf16 v[124:127], v[146:149], v[190:193], 0
	v_mfma_f32_16x16x32_bf16 v[120:123], v[154:157], v[190:193], 0
	v_mfma_f32_16x16x32_bf16 v[108:111], v[146:149], v[198:201], 0
	v_mfma_f32_16x16x32_bf16 v[104:107], v[154:157], v[198:201], 0
	v_mfma_f32_16x16x32_bf16 v[92:95], v[146:149], v[206:209], 0
	v_mfma_f32_16x16x32_bf16 v[88:91], v[154:157], v[206:209], 0
	v_mfma_f32_16x16x32_bf16 v[76:79], v[146:149], v[218:221], 0
	v_mfma_f32_16x16x32_bf16 v[72:75], v[154:157], v[218:221], 0
	v_mfma_f32_16x16x32_bf16 v[124:127], v[150:153], v[194:197], v[124:127]
	v_mfma_f32_16x16x32_bf16 v[120:123], v[170:173], v[194:197], v[120:123]
	v_mfma_f32_16x16x32_bf16 v[108:111], v[150:153], v[202:205], v[108:111]
	v_mfma_f32_16x16x32_bf16 v[104:107], v[170:173], v[202:205], v[104:107]
	v_mfma_f32_16x16x32_bf16 v[92:95], v[150:153], v[214:217], v[92:95]
	v_mfma_f32_16x16x32_bf16 v[88:91], v[170:173], v[214:217], v[88:91]
	v_mfma_f32_16x16x32_bf16 v[76:79], v[150:153], v[222:225], v[76:79]
	v_mfma_f32_16x16x32_bf16 v[72:75], v[170:173], v[222:225], v[72:75]
	s_setprio 0
	s_setprio 1
	v_mfma_f32_16x16x32_bf16 v[116:119], v[174:177], v[190:193], 0
	v_mfma_f32_16x16x32_bf16 v[112:115], v[182:185], v[190:193], 0
	v_mfma_f32_16x16x32_bf16 v[100:103], v[174:177], v[198:201], 0
	v_mfma_f32_16x16x32_bf16 v[96:99], v[182:185], v[198:201], 0
	v_mfma_f32_16x16x32_bf16 v[84:87], v[174:177], v[206:209], 0
	v_mfma_f32_16x16x32_bf16 v[80:83], v[182:185], v[206:209], 0
	v_mfma_f32_16x16x32_bf16 v[68:71], v[174:177], v[218:221], 0
	v_mfma_f32_16x16x32_bf16 v[64:67], v[182:185], v[218:221], 0
	v_mfma_f32_16x16x32_bf16 v[116:119], v[178:181], v[194:197], v[116:119]
	v_mfma_f32_16x16x32_bf16 v[112:115], v[186:189], v[194:197], v[112:115]
	v_mfma_f32_16x16x32_bf16 v[100:103], v[178:181], v[202:205], v[100:103]
	v_mfma_f32_16x16x32_bf16 v[96:99], v[186:189], v[202:205], v[96:99]
	v_mfma_f32_16x16x32_bf16 v[84:87], v[178:181], v[214:217], v[84:87]
	v_mfma_f32_16x16x32_bf16 v[80:83], v[186:189], v[214:217], v[80:83]
	v_mfma_f32_16x16x32_bf16 v[68:71], v[178:181], v[222:225], v[68:71]
	v_mfma_f32_16x16x32_bf16 v[64:67], v[186:189], v[222:225], v[64:67]
	s_setprio 0
	s_barrier
	s_add_i32 s91, s81, s30
	v_lshl_add_u64 v[158:159], s[76:77], 0, v[130:131]
	s_mov_b32 m0, s91
	ds_read_b128 v[190:193], v168 offset:16384
	ds_read_b128 v[194:197], v168 offset:17408
	ds_read_b128 v[198:201], v168 offset:18432
	ds_read_b128 v[202:205], v168 offset:19456
	ds_read_b128 v[206:209], v168 offset:20480
	ds_read_b128 v[214:217], v168 offset:21504
	ds_read_b128 v[218:221], v168 offset:22528
	ds_read_b128 v[222:225], v168 offset:23552
	global_load_lds_dwordx4 v[158:159], off
	s_add_i32 m0, s91, 0x2000
	s_add_u32 s92, s76, 0x80000
	v_lshl_add_u64 v[210:211], s[76:77], 0, v[134:135]
	s_addc_u32 s93, s77, 0
	s_add_i32 s91, s83, s30
	global_load_lds_dwordx4 v[210:211], off
	v_lshl_add_u64 v[226:227], s[92:93], 0, v[130:131]
	s_mov_b32 m0, s91
	v_lshl_add_u64 v[228:229], s[78:79], 0, v[132:133]
	global_load_lds_dwordx4 v[226:227], off
	v_lshl_add_u64 v[226:227], s[92:93], 0, v[134:135]
	s_add_i32 m0, s91, 0x2000
	s_nop 0
	global_load_lds_dwordx4 v[226:227], off
	v_lshl_add_u64 v[226:227], s[78:79], 0, v[128:129]
	s_mov_b32 m0, s31
	s_nop 0
	global_load_lds_dwordx4 v[226:227], off
	s_mov_b32 m0, s51
	s_nop 0
	global_load_lds_dwordx4 v[228:229], off
	s_waitcnt vmcnt(8)
	s_waitcnt lgkmcnt(0)
	s_barrier
	s_setprio 1
	s_waitcnt lgkmcnt(0)
	v_mfma_f32_16x16x32_bf16 v[60:63], v[146:149], v[190:193], 0
	v_mfma_f32_16x16x32_bf16 v[56:59], v[154:157], v[190:193], 0
	v_mfma_f32_16x16x32_bf16 v[44:47], v[146:149], v[198:201], 0
	v_mfma_f32_16x16x32_bf16 v[40:43], v[154:157], v[198:201], 0
	v_mfma_f32_16x16x32_bf16 v[28:31], v[146:149], v[206:209], 0
	v_mfma_f32_16x16x32_bf16 v[24:27], v[154:157], v[206:209], 0
	v_mfma_f32_16x16x32_bf16 v[12:15], v[146:149], v[218:221], 0
	v_mfma_f32_16x16x32_bf16 v[8:11], v[154:157], v[218:221], 0
	v_mfma_f32_16x16x32_bf16 v[60:63], v[150:153], v[194:197], v[60:63]
	v_mfma_f32_16x16x32_bf16 v[56:59], v[170:173], v[194:197], v[56:59]
	v_mfma_f32_16x16x32_bf16 v[44:47], v[150:153], v[202:205], v[44:47]
	v_mfma_f32_16x16x32_bf16 v[40:43], v[170:173], v[202:205], v[40:43]
	v_mfma_f32_16x16x32_bf16 v[28:31], v[150:153], v[214:217], v[28:31]
	v_mfma_f32_16x16x32_bf16 v[24:27], v[170:173], v[214:217], v[24:27]
	v_mfma_f32_16x16x32_bf16 v[12:15], v[150:153], v[222:225], v[12:15]
	v_mfma_f32_16x16x32_bf16 v[8:11], v[170:173], v[222:225], v[8:11]
	s_setprio 0
	s_setprio 1
	v_mfma_f32_16x16x32_bf16 v[52:55], v[174:177], v[190:193], 0
	v_mfma_f32_16x16x32_bf16 v[48:51], v[182:185], v[190:193], 0
	v_mfma_f32_16x16x32_bf16 v[36:39], v[174:177], v[198:201], 0
	v_mfma_f32_16x16x32_bf16 v[32:35], v[182:185], v[198:201], 0
	v_mfma_f32_16x16x32_bf16 v[20:23], v[174:177], v[206:209], 0
	v_mfma_f32_16x16x32_bf16 v[16:19], v[182:185], v[206:209], 0
	v_mfma_f32_16x16x32_bf16 v[4:7], v[174:177], v[218:221], 0
	v_mfma_f32_16x16x32_bf16 v[0:3], v[182:185], v[218:221], 0
	v_mfma_f32_16x16x32_bf16 v[52:55], v[178:181], v[194:197], v[52:55]
	v_mfma_f32_16x16x32_bf16 v[48:51], v[186:189], v[194:197], v[48:51]
	v_mfma_f32_16x16x32_bf16 v[36:39], v[178:181], v[202:205], v[36:39]
	v_mfma_f32_16x16x32_bf16 v[32:35], v[186:189], v[202:205], v[32:35]
	v_mfma_f32_16x16x32_bf16 v[20:23], v[178:181], v[214:217], v[20:23]
	v_mfma_f32_16x16x32_bf16 v[16:19], v[186:189], v[214:217], v[16:19]
	v_mfma_f32_16x16x32_bf16 v[4:7], v[178:181], v[222:225], v[4:7]
	v_mfma_f32_16x16x32_bf16 v[0:3], v[186:189], v[222:225], v[0:3]
	s_setprio 0
	s_barrier
	s_add_i32 s91, 0, 0x18000
	v_add_u32_e32 v136, s91, v162
	s_add_i32 s92, 0, 0x1c000
	ds_read_b128 v[146:149], v136
	ds_read_b128 v[150:153], v136 offset:1024
	ds_read_b128 v[154:157], v136 offset:2048
	ds_read_b128 v[170:173], v136 offset:3072
	v_add_u32_e32 v136, s92, v162
	ds_read_b128 v[174:177], v136
	ds_read_b128 v[178:181], v136 offset:1024
	ds_read_b128 v[182:185], v136 offset:2048
	ds_read_b128 v[186:189], v136 offset:3072
	s_add_u32 s78, s78, 0x80000
	s_addc_u32 s79, s79, 0
	s_mov_b32 m0, s28
	v_lshl_add_u64 v[230:231], s[78:79], 0, v[128:129]
	ds_read_b128 v[190:193], v168 offset:32768
	ds_read_b128 v[194:197], v168 offset:33792
	ds_read_b128 v[198:201], v168 offset:34816
	ds_read_b128 v[202:205], v168 offset:35840
	ds_read_b128 v[206:209], v168 offset:36864
	ds_read_b128 v[214:217], v168 offset:37888
	ds_read_b128 v[218:221], v168 offset:38912
	ds_read_b128 v[222:225], v168 offset:39936
	global_load_lds_dwordx4 v[230:231], off
	v_lshl_add_u64 v[230:231], s[78:79], 0, v[132:133]
	s_mov_b32 m0, s29
	s_nop 0
	global_load_lds_dwordx4 v[230:231], off
	s_waitcnt vmcnt(8)
	s_waitcnt lgkmcnt(0)
	s_barrier
	s_setprio 1
	s_waitcnt lgkmcnt(0)
	v_mfma_f32_16x16x32_bf16 v[124:127], v[146:149], v[190:193], v[124:127]
	v_mfma_f32_16x16x32_bf16 v[120:123], v[154:157], v[190:193], v[120:123]
	v_mfma_f32_16x16x32_bf16 v[108:111], v[146:149], v[198:201], v[108:111]
	v_mfma_f32_16x16x32_bf16 v[104:107], v[154:157], v[198:201], v[104:107]
	v_mfma_f32_16x16x32_bf16 v[92:95], v[146:149], v[206:209], v[92:95]
	v_mfma_f32_16x16x32_bf16 v[88:91], v[154:157], v[206:209], v[88:91]
	v_mfma_f32_16x16x32_bf16 v[76:79], v[146:149], v[218:221], v[76:79]
	v_mfma_f32_16x16x32_bf16 v[72:75], v[154:157], v[218:221], v[72:75]
	v_mfma_f32_16x16x32_bf16 v[124:127], v[150:153], v[194:197], v[124:127]
	v_mfma_f32_16x16x32_bf16 v[120:123], v[170:173], v[194:197], v[120:123]
	v_mfma_f32_16x16x32_bf16 v[108:111], v[150:153], v[202:205], v[108:111]
	v_mfma_f32_16x16x32_bf16 v[104:107], v[170:173], v[202:205], v[104:107]
	v_mfma_f32_16x16x32_bf16 v[92:95], v[150:153], v[214:217], v[92:95]
	v_mfma_f32_16x16x32_bf16 v[88:91], v[170:173], v[214:217], v[88:91]
	v_mfma_f32_16x16x32_bf16 v[76:79], v[150:153], v[222:225], v[76:79]
	v_mfma_f32_16x16x32_bf16 v[72:75], v[170:173], v[222:225], v[72:75]
	s_setprio 0
	s_setprio 1
	v_mfma_f32_16x16x32_bf16 v[116:119], v[174:177], v[190:193], v[116:119]
	v_mfma_f32_16x16x32_bf16 v[112:115], v[182:185], v[190:193], v[112:115]
	v_mfma_f32_16x16x32_bf16 v[100:103], v[174:177], v[198:201], v[100:103]
	v_mfma_f32_16x16x32_bf16 v[96:99], v[182:185], v[198:201], v[96:99]
	v_mfma_f32_16x16x32_bf16 v[84:87], v[174:177], v[206:209], v[84:87]
	v_mfma_f32_16x16x32_bf16 v[80:83], v[182:185], v[206:209], v[80:83]
	v_mfma_f32_16x16x32_bf16 v[68:71], v[174:177], v[218:221], v[68:71]
	v_mfma_f32_16x16x32_bf16 v[64:67], v[182:185], v[218:221], v[64:67]
	v_mfma_f32_16x16x32_bf16 v[116:119], v[178:181], v[194:197], v[116:119]
	v_mfma_f32_16x16x32_bf16 v[112:115], v[186:189], v[194:197], v[112:115]
	v_mfma_f32_16x16x32_bf16 v[100:103], v[178:181], v[202:205], v[100:103]
	v_mfma_f32_16x16x32_bf16 v[96:99], v[186:189], v[202:205], v[96:99]
	v_mfma_f32_16x16x32_bf16 v[84:87], v[178:181], v[214:217], v[84:87]
	v_mfma_f32_16x16x32_bf16 v[80:83], v[186:189], v[214:217], v[80:83]
	v_mfma_f32_16x16x32_bf16 v[68:71], v[178:181], v[222:225], v[68:71]
	v_mfma_f32_16x16x32_bf16 v[64:67], v[186:189], v[222:225], v[64:67]
	s_setprio 0
	s_barrier
	s_add_i32 s78, s91, s30
	v_lshl_add_u64 v[158:159], v[158:159], 0, s[34:35]
	s_mov_b32 m0, s78
	ds_read_b128 v[190:193], v168 offset:49152
	ds_read_b128 v[194:197], v168 offset:50176
	ds_read_b128 v[198:201], v168 offset:51200
	ds_read_b128 v[202:205], v168 offset:52224
	ds_read_b128 v[206:209], v168 offset:53248
	ds_read_b128 v[214:217], v168 offset:54272
	ds_read_b128 v[218:221], v168 offset:55296
	ds_read_b128 v[222:225], v168 offset:56320
	global_load_lds_dwordx4 v[158:159], off
	s_add_i32 m0, s78, 0x2000
	s_add_u32 s76, s76, 0x80080
	v_lshl_add_u64 v[158:159], v[210:211], 0, s[34:35]
	s_addc_u32 s77, s77, 0
	s_add_i32 s78, s92, s30
	global_load_lds_dwordx4 v[158:159], off
	v_lshl_add_u64 v[158:159], s[76:77], 0, v[130:131]
	s_mov_b32 m0, s78
	s_nop 0
	global_load_lds_dwordx4 v[158:159], off
	v_lshl_add_u64 v[158:159], s[76:77], 0, v[134:135]
	s_add_i32 m0, s78, 0x2000
	s_nop 0
	global_load_lds_dwordx4 v[158:159], off
	v_lshl_add_u64 v[158:159], v[226:227], 0, s[34:35]
	s_mov_b32 m0, s73
	s_nop 0
	global_load_lds_dwordx4 v[158:159], off
	v_lshl_add_u64 v[158:159], v[228:229], 0, s[34:35]
	s_mov_b32 m0, s80
	s_nop 0
	global_load_lds_dwordx4 v[158:159], off
	s_waitcnt vmcnt(8)
	s_waitcnt lgkmcnt(0)
	s_barrier
	s_setprio 1
	s_waitcnt lgkmcnt(0)
	v_mfma_f32_16x16x32_bf16 v[60:63], v[146:149], v[190:193], v[60:63]
	v_mfma_f32_16x16x32_bf16 v[56:59], v[154:157], v[190:193], v[56:59]
	v_mfma_f32_16x16x32_bf16 v[44:47], v[146:149], v[198:201], v[44:47]
	v_mfma_f32_16x16x32_bf16 v[40:43], v[154:157], v[198:201], v[40:43]
	v_mfma_f32_16x16x32_bf16 v[28:31], v[146:149], v[206:209], v[28:31]
	v_mfma_f32_16x16x32_bf16 v[24:27], v[154:157], v[206:209], v[24:27]
	v_mfma_f32_16x16x32_bf16 v[12:15], v[146:149], v[218:221], v[12:15]
	v_mfma_f32_16x16x32_bf16 v[8:11], v[154:157], v[218:221], v[8:11]
	v_mfma_f32_16x16x32_bf16 v[60:63], v[150:153], v[194:197], v[60:63]
	v_mfma_f32_16x16x32_bf16 v[56:59], v[170:173], v[194:197], v[56:59]
	v_mfma_f32_16x16x32_bf16 v[44:47], v[150:153], v[202:205], v[44:47]
	v_mfma_f32_16x16x32_bf16 v[40:43], v[170:173], v[202:205], v[40:43]
	v_mfma_f32_16x16x32_bf16 v[28:31], v[150:153], v[214:217], v[28:31]
	v_mfma_f32_16x16x32_bf16 v[24:27], v[170:173], v[214:217], v[24:27]
	v_mfma_f32_16x16x32_bf16 v[12:15], v[150:153], v[222:225], v[12:15]
	v_mfma_f32_16x16x32_bf16 v[8:11], v[170:173], v[222:225], v[8:11]
	s_setprio 0
	s_setprio 1
	v_mfma_f32_16x16x32_bf16 v[52:55], v[174:177], v[190:193], v[52:55]
	v_mfma_f32_16x16x32_bf16 v[48:51], v[182:185], v[190:193], v[48:51]
	v_mfma_f32_16x16x32_bf16 v[36:39], v[174:177], v[198:201], v[36:39]
	v_mfma_f32_16x16x32_bf16 v[32:35], v[182:185], v[198:201], v[32:35]
	v_mfma_f32_16x16x32_bf16 v[20:23], v[174:177], v[206:209], v[20:23]
	v_mfma_f32_16x16x32_bf16 v[16:19], v[182:185], v[206:209], v[16:19]
	v_mfma_f32_16x16x32_bf16 v[4:7], v[174:177], v[218:221], v[4:7]
	v_mfma_f32_16x16x32_bf16 v[0:3], v[182:185], v[218:221], v[0:3]
	v_mfma_f32_16x16x32_bf16 v[52:55], v[178:181], v[194:197], v[52:55]
	v_mfma_f32_16x16x32_bf16 v[48:51], v[186:189], v[194:197], v[48:51]
	v_mfma_f32_16x16x32_bf16 v[36:39], v[178:181], v[202:205], v[36:39]
	v_mfma_f32_16x16x32_bf16 v[32:35], v[186:189], v[202:205], v[32:35]
	v_mfma_f32_16x16x32_bf16 v[20:23], v[178:181], v[214:217], v[20:23]
	v_mfma_f32_16x16x32_bf16 v[16:19], v[186:189], v[214:217], v[16:19]
	v_mfma_f32_16x16x32_bf16 v[4:7], v[178:181], v[222:225], v[4:7]
	v_mfma_f32_16x16x32_bf16 v[0:3], v[186:189], v[222:225], v[0:3]
	s_setprio 0
	s_barrier
	s_add_i32 s90, s90, 2
	s_add_u32 s74, s74, 0x100
	s_addc_u32 s75, s75, 0
	s_add_u32 s65, s65, 0x100
	s_addc_u32 s71, s71, 0
	s_cmp_gt_u32 s90, 29

.LBB0_542:
	s_ashr_i32 s35, s34, 31
	s_lshl_b64 s[0:1], s[34:35], 20
	s_add_u32 s36, s29, s0
	s_addc_u32 s37, s30, s1
	s_and_b64 s[0:1], s[6:7], exec
	s_cselect_b32 s0, s37, s43
	s_cselect_b32 s1, s36, s42
	s_ashr_i32 s25, s24, 31
	s_lshl_b64 s[38:39], s[24:25], 20
	s_add_u32 s38, s27, s38
	s_addc_u32 s39, s28, s39
	s_and_b64 s[46:47], s[6:7], exec
	s_cselect_b32 s3, s39, s45
	s_cselect_b32 s9, s38, s44
	s_add_u32 s42, s42, 0x80080
	s_addc_u32 s43, s43, 0
	s_add_u32 s25, s44, 0x100
	s_addc_u32 s35, s45, 0
	s_mov_b32 s58, -2
	s_waitcnt lgkmcnt(0)
	s_waitcnt vmcnt(0)
	ds_read_b128 v[128:131], v216
	ds_read_b128 v[132:135], v216 offset:1024
	ds_read_b128 v[136:139], v216 offset:2048
	ds_read_b128 v[140:143], v216 offset:3072
	ds_read_b128 v[144:147], v217
	ds_read_b128 v[148:151], v217 offset:1024
	ds_read_b128 v[152:155], v217 offset:2048
	ds_read_b128 v[156:159], v217 offset:3072
	s_add_u32 s44, s42, 0xfff80080
	s_addc_u32 s45, s43, -1
	s_cmp_eq_u32 s58, 28
	s_cselect_b32 s47, s0, s45
	s_cselect_b32 s46, s1, s44
	s_cselect_b32 s45, s3, s35
	s_cselect_b32 s44, s9, s25
	v_lshl_add_u64 v[208:209], s[42:43], 0, v[184:185]
	s_add_i32 m0, s41, 0xc000
	ds_read_b128 v[160:163], v218
	ds_read_b128 v[164:167], v218 offset:1024
	ds_read_b128 v[168:171], v218 offset:2048
	ds_read_b128 v[172:175], v218 offset:3072
	ds_read_b128 v[192:195], v218 offset:4096
	ds_read_b128 v[196:199], v218 offset:5120
	ds_read_b128 v[200:203], v218 offset:6144
	ds_read_b128 v[204:207], v218 offset:7168
	global_load_lds_dwordx4 v[208:209], off
	v_lshl_add_u64 v[208:209], s[42:43], 0, v[186:187]
	s_add_i32 m0, s41, 0xe000
	s_nop 0
	global_load_lds_dwordx4 v[208:209], off
	s_waitcnt vmcnt(8)
	s_waitcnt lgkmcnt(0)
	s_barrier
	s_setprio 1
	s_waitcnt lgkmcnt(0)
	v_mfma_f32_16x16x32_bf16 v[124:127], v[128:131], v[160:163], 0
	v_mfma_f32_16x16x32_bf16 v[120:123], v[136:139], v[160:163], 0
	v_mfma_f32_16x16x32_bf16 v[108:111], v[128:131], v[168:171], 0
	v_mfma_f32_16x16x32_bf16 v[104:107], v[136:139], v[168:171], 0
	v_mfma_f32_16x16x32_bf16 v[92:95], v[128:131], v[192:195], 0
	v_mfma_f32_16x16x32_bf16 v[88:91], v[136:139], v[192:195], 0
	v_mfma_f32_16x16x32_bf16 v[76:79], v[128:131], v[200:203], 0
	v_mfma_f32_16x16x32_bf16 v[72:75], v[136:139], v[200:203], 0
	v_mfma_f32_16x16x32_bf16 v[124:127], v[132:135], v[164:167], v[124:127]
	v_mfma_f32_16x16x32_bf16 v[120:123], v[140:143], v[164:167], v[120:123]
	v_mfma_f32_16x16x32_bf16 v[108:111], v[132:135], v[172:175], v[108:111]
	v_mfma_f32_16x16x32_bf16 v[104:107], v[140:143], v[172:175], v[104:107]
	v_mfma_f32_16x16x32_bf16 v[92:95], v[132:135], v[196:199], v[92:95]
	v_mfma_f32_16x16x32_bf16 v[88:91], v[140:143], v[196:199], v[88:91]
	v_mfma_f32_16x16x32_bf16 v[76:79], v[132:135], v[204:207], v[76:79]
	v_mfma_f32_16x16x32_bf16 v[72:75], v[140:143], v[204:207], v[72:75]
	s_setprio 0
	s_setprio 1
	v_mfma_f32_16x16x32_bf16 v[116:119], v[144:147], v[160:163], 0
	v_mfma_f32_16x16x32_bf16 v[112:115], v[152:155], v[160:163], 0
	v_mfma_f32_16x16x32_bf16 v[100:103], v[144:147], v[168:171], 0
	v_mfma_f32_16x16x32_bf16 v[96:99], v[152:155], v[168:171], 0
	v_mfma_f32_16x16x32_bf16 v[84:87], v[144:147], v[192:195], 0
	v_mfma_f32_16x16x32_bf16 v[80:83], v[152:155], v[192:195], 0
	v_mfma_f32_16x16x32_bf16 v[68:71], v[144:147], v[200:203], 0
	v_mfma_f32_16x16x32_bf16 v[64:67], v[152:155], v[200:203], 0
	v_mfma_f32_16x16x32_bf16 v[116:119], v[148:151], v[164:167], v[116:119]
	v_mfma_f32_16x16x32_bf16 v[112:115], v[156:159], v[164:167], v[112:115]
	v_mfma_f32_16x16x32_bf16 v[100:103], v[148:151], v[172:175], v[100:103]
	v_mfma_f32_16x16x32_bf16 v[96:99], v[156:159], v[172:175], v[96:99]
	v_mfma_f32_16x16x32_bf16 v[84:87], v[148:151], v[196:199], v[84:87]
	v_mfma_f32_16x16x32_bf16 v[80:83], v[156:159], v[196:199], v[80:83]
	v_mfma_f32_16x16x32_bf16 v[68:71], v[148:151], v[204:207], v[68:71]
	v_mfma_f32_16x16x32_bf16 v[64:67], v[156:159], v[204:207], v[64:67]
	s_setprio 0
	s_barrier
	s_add_i32 s59, s55, s31
	v_lshl_add_u64 v[208:209], s[44:45], 0, v[178:179]
	s_mov_b32 m0, s59
	ds_read_b128 v[160:163], v218 offset:16384
	ds_read_b128 v[164:167], v218 offset:17408
	ds_read_b128 v[168:171], v218 offset:18432
	ds_read_b128 v[172:175], v218 offset:19456
	ds_read_b128 v[192:195], v218 offset:20480
	ds_read_b128 v[196:199], v218 offset:21504
	ds_read_b128 v[200:203], v218 offset:22528
	ds_read_b128 v[204:207], v218 offset:23552
	global_load_lds_dwordx4 v[208:209], off
	s_add_i32 m0, s59, 0x2000
	s_add_u32 s60, s44, 0x80000
	v_lshl_add_u64 v[210:211], s[44:45], 0, v[182:183]
	s_addc_u32 s61, s45, 0
	s_add_i32 s59, s56, s31
	global_load_lds_dwordx4 v[210:211], off
	v_lshl_add_u64 v[222:223], s[60:61], 0, v[178:179]
	s_mov_b32 m0, s59
	v_lshl_add_u64 v[224:225], s[46:47], 0, v[180:181]
	global_load_lds_dwordx4 v[222:223], off
	v_lshl_add_u64 v[222:223], s[60:61], 0, v[182:183]
	s_add_i32 m0, s59, 0x2000
	s_nop 0
	global_load_lds_dwordx4 v[222:223], off
	v_lshl_add_u64 v[222:223], s[46:47], 0, v[176:177]
	s_mov_b32 m0, s41
	s_nop 0
	global_load_lds_dwordx4 v[222:223], off
	s_mov_b32 m0, s48
	s_nop 0
	global_load_lds_dwordx4 v[224:225], off
	s_waitcnt vmcnt(8)
	s_waitcnt lgkmcnt(0)
	s_barrier
	s_setprio 1
	s_waitcnt lgkmcnt(0)
	v_mfma_f32_16x16x32_bf16 v[60:63], v[128:131], v[160:163], 0
	v_mfma_f32_16x16x32_bf16 v[56:59], v[136:139], v[160:163], 0
	v_mfma_f32_16x16x32_bf16 v[44:47], v[128:131], v[168:171], 0
	v_mfma_f32_16x16x32_bf16 v[40:43], v[136:139], v[168:171], 0
	v_mfma_f32_16x16x32_bf16 v[28:31], v[128:131], v[192:195], 0
	v_mfma_f32_16x16x32_bf16 v[24:27], v[136:139], v[192:195], 0
	v_mfma_f32_16x16x32_bf16 v[12:15], v[128:131], v[200:203], 0
	v_mfma_f32_16x16x32_bf16 v[8:11], v[136:139], v[200:203], 0
	v_mfma_f32_16x16x32_bf16 v[60:63], v[132:135], v[164:167], v[60:63]
	v_mfma_f32_16x16x32_bf16 v[56:59], v[140:143], v[164:167], v[56:59]
	v_mfma_f32_16x16x32_bf16 v[44:47], v[132:135], v[172:175], v[44:47]
	v_mfma_f32_16x16x32_bf16 v[40:43], v[140:143], v[172:175], v[40:43]
	v_mfma_f32_16x16x32_bf16 v[28:31], v[132:135], v[196:199], v[28:31]
	v_mfma_f32_16x16x32_bf16 v[24:27], v[140:143], v[196:199], v[24:27]
	v_mfma_f32_16x16x32_bf16 v[12:15], v[132:135], v[204:207], v[12:15]
	v_mfma_f32_16x16x32_bf16 v[8:11], v[140:143], v[204:207], v[8:11]
	s_setprio 0
	s_setprio 1
	v_mfma_f32_16x16x32_bf16 v[52:55], v[144:147], v[160:163], 0
	v_mfma_f32_16x16x32_bf16 v[48:51], v[152:155], v[160:163], 0
	v_mfma_f32_16x16x32_bf16 v[36:39], v[144:147], v[168:171], 0
	v_mfma_f32_16x16x32_bf16 v[32:35], v[152:155], v[168:171], 0
	v_mfma_f32_16x16x32_bf16 v[20:23], v[144:147], v[192:195], 0
	v_mfma_f32_16x16x32_bf16 v[16:19], v[152:155], v[192:195], 0
	v_mfma_f32_16x16x32_bf16 v[4:7], v[144:147], v[200:203], 0
	v_mfma_f32_16x16x32_bf16 v[0:3], v[152:155], v[200:203], 0
	v_mfma_f32_16x16x32_bf16 v[52:55], v[148:151], v[164:167], v[52:55]
	v_mfma_f32_16x16x32_bf16 v[48:51], v[156:159], v[164:167], v[48:51]
	v_mfma_f32_16x16x32_bf16 v[36:39], v[148:151], v[172:175], v[36:39]
	v_mfma_f32_16x16x32_bf16 v[32:35], v[156:159], v[172:175], v[32:35]
	v_mfma_f32_16x16x32_bf16 v[20:23], v[148:151], v[196:199], v[20:23]
	v_mfma_f32_16x16x32_bf16 v[16:19], v[156:159], v[196:199], v[16:19]
	v_mfma_f32_16x16x32_bf16 v[4:7], v[148:151], v[204:207], v[4:7]
	v_mfma_f32_16x16x32_bf16 v[0:3], v[156:159], v[204:207], v[0:3]
	s_setprio 0
	s_barrier
	s_add_i32 s59, 0, 0x18000
	s_add_i32 s60, 0, 0x1c000
	v_add_u32_e32 v140, s59, v214
	v_add_u32_e32 v156, s60, v214
	ds_read_b128 v[128:131], v140
	ds_read_b128 v[132:135], v140 offset:1024
	ds_read_b128 v[136:139], v140 offset:2048
	ds_read_b128 v[140:143], v140 offset:3072
	ds_read_b128 v[144:147], v156
	ds_read_b128 v[148:151], v156 offset:1024
	ds_read_b128 v[152:155], v156 offset:2048
	ds_read_b128 v[156:159], v156 offset:3072
	s_add_u32 s46, s46, 0x80000
	s_addc_u32 s47, s47, 0
	s_mov_b32 m0, s49
	v_lshl_add_u64 v[226:227], s[46:47], 0, v[176:177]
	ds_read_b128 v[160:163], v218 offset:32768
	ds_read_b128 v[164:167], v218 offset:33792
	ds_read_b128 v[168:171], v218 offset:34816
	ds_read_b128 v[172:175], v218 offset:35840
	ds_read_b128 v[192:195], v218 offset:36864
	ds_read_b128 v[196:199], v218 offset:37888
	ds_read_b128 v[200:203], v218 offset:38912
	ds_read_b128 v[204:207], v218 offset:39936
	global_load_lds_dwordx4 v[226:227], off
	v_lshl_add_u64 v[226:227], s[46:47], 0, v[180:181]
	s_mov_b32 m0, s50
	s_nop 0
	global_load_lds_dwordx4 v[226:227], off
	s_waitcnt vmcnt(8)
	s_waitcnt lgkmcnt(0)
	s_barrier
	s_setprio 1
	s_waitcnt lgkmcnt(0)
	v_mfma_f32_16x16x32_bf16 v[124:127], v[128:131], v[160:163], v[124:127]
	v_mfma_f32_16x16x32_bf16 v[120:123], v[136:139], v[160:163], v[120:123]
	v_mfma_f32_16x16x32_bf16 v[108:111], v[128:131], v[168:171], v[108:111]
	v_mfma_f32_16x16x32_bf16 v[104:107], v[136:139], v[168:171], v[104:107]
	v_mfma_f32_16x16x32_bf16 v[92:95], v[128:131], v[192:195], v[92:95]
	v_mfma_f32_16x16x32_bf16 v[88:91], v[136:139], v[192:195], v[88:91]
	v_mfma_f32_16x16x32_bf16 v[76:79], v[128:131], v[200:203], v[76:79]
	v_mfma_f32_16x16x32_bf16 v[72:75], v[136:139], v[200:203], v[72:75]
	v_mfma_f32_16x16x32_bf16 v[124:127], v[132:135], v[164:167], v[124:127]
	v_mfma_f32_16x16x32_bf16 v[120:123], v[140:143], v[164:167], v[120:123]
	v_mfma_f32_16x16x32_bf16 v[108:111], v[132:135], v[172:175], v[108:111]
	v_mfma_f32_16x16x32_bf16 v[104:107], v[140:143], v[172:175], v[104:107]
	v_mfma_f32_16x16x32_bf16 v[92:95], v[132:135], v[196:199], v[92:95]
	v_mfma_f32_16x16x32_bf16 v[88:91], v[140:143], v[196:199], v[88:91]
	v_mfma_f32_16x16x32_bf16 v[76:79], v[132:135], v[204:207], v[76:79]
	v_mfma_f32_16x16x32_bf16 v[72:75], v[140:143], v[204:207], v[72:75]
	s_setprio 0
	s_setprio 1
	v_mfma_f32_16x16x32_bf16 v[116:119], v[144:147], v[160:163], v[116:119]
	v_mfma_f32_16x16x32_bf16 v[112:115], v[152:155], v[160:163], v[112:115]
	v_mfma_f32_16x16x32_bf16 v[100:103], v[144:147], v[168:171], v[100:103]
	v_mfma_f32_16x16x32_bf16 v[96:99], v[152:155], v[168:171], v[96:99]
	v_mfma_f32_16x16x32_bf16 v[84:87], v[144:147], v[192:195], v[84:87]
	v_mfma_f32_16x16x32_bf16 v[80:83], v[152:155], v[192:195], v[80:83]
	v_mfma_f32_16x16x32_bf16 v[68:71], v[144:147], v[200:203], v[68:71]
	v_mfma_f32_16x16x32_bf16 v[64:67], v[152:155], v[200:203], v[64:67]
	v_mfma_f32_16x16x32_bf16 v[116:119], v[148:151], v[164:167], v[116:119]
	v_mfma_f32_16x16x32_bf16 v[112:115], v[156:159], v[164:167], v[112:115]
	v_mfma_f32_16x16x32_bf16 v[100:103], v[148:151], v[172:175], v[100:103]
	v_mfma_f32_16x16x32_bf16 v[96:99], v[156:159], v[172:175], v[96:99]
	v_mfma_f32_16x16x32_bf16 v[84:87], v[148:151], v[196:199], v[84:87]
	v_mfma_f32_16x16x32_bf16 v[80:83], v[156:159], v[196:199], v[80:83]
	v_mfma_f32_16x16x32_bf16 v[68:71], v[148:151], v[204:207], v[68:71]
	v_mfma_f32_16x16x32_bf16 v[64:67], v[156:159], v[204:207], v[64:67]
	s_setprio 0
	s_barrier
	s_add_i32 s46, s59, s31
	v_lshl_add_u64 v[208:209], v[208:209], 0, s[20:21]
	s_mov_b32 m0, s46
	ds_read_b128 v[160:163], v218 offset:49152
	ds_read_b128 v[164:167], v218 offset:50176
	ds_read_b128 v[168:171], v218 offset:51200
	ds_read_b128 v[172:175], v218 offset:52224
	ds_read_b128 v[192:195], v218 offset:53248
	ds_read_b128 v[196:199], v218 offset:54272
	ds_read_b128 v[200:203], v218 offset:55296
	ds_read_b128 v[204:207], v218 offset:56320
	global_load_lds_dwordx4 v[208:209], off
	s_add_i32 m0, s46, 0x2000
	s_add_u32 s44, s44, 0x80080
	v_lshl_add_u64 v[208:209], v[210:211], 0, s[20:21]
	s_addc_u32 s45, s45, 0
	s_add_i32 s46, s60, s31
	global_load_lds_dwordx4 v[208:209], off
	v_lshl_add_u64 v[208:209], s[44:45], 0, v[178:179]
	s_mov_b32 m0, s46
	s_nop 0
	global_load_lds_dwordx4 v[208:209], off
	v_lshl_add_u64 v[208:209], s[44:45], 0, v[182:183]
	s_add_i32 m0, s46, 0x2000
	s_nop 0
	global_load_lds_dwordx4 v[208:209], off
	v_lshl_add_u64 v[208:209], v[222:223], 0, s[20:21]
	s_mov_b32 m0, s52
	s_nop 0
	global_load_lds_dwordx4 v[208:209], off
	v_lshl_add_u64 v[208:209], v[224:225], 0, s[20:21]
	s_mov_b32 m0, s53
	s_nop 0
	global_load_lds_dwordx4 v[208:209], off
	s_waitcnt vmcnt(8)
	s_waitcnt lgkmcnt(0)
	s_barrier
	s_setprio 1
	s_waitcnt lgkmcnt(0)
	v_mfma_f32_16x16x32_bf16 v[60:63], v[128:131], v[160:163], v[60:63]
	v_mfma_f32_16x16x32_bf16 v[56:59], v[136:139], v[160:163], v[56:59]
	v_mfma_f32_16x16x32_bf16 v[44:47], v[128:131], v[168:171], v[44:47]
	v_mfma_f32_16x16x32_bf16 v[40:43], v[136:139], v[168:171], v[40:43]
	v_mfma_f32_16x16x32_bf16 v[28:31], v[128:131], v[192:195], v[28:31]
	v_mfma_f32_16x16x32_bf16 v[24:27], v[136:139], v[192:195], v[24:27]
	v_mfma_f32_16x16x32_bf16 v[12:15], v[128:131], v[200:203], v[12:15]
	v_mfma_f32_16x16x32_bf16 v[8:11], v[136:139], v[200:203], v[8:11]
	v_mfma_f32_16x16x32_bf16 v[60:63], v[132:135], v[164:167], v[60:63]
	v_mfma_f32_16x16x32_bf16 v[56:59], v[140:143], v[164:167], v[56:59]
	v_mfma_f32_16x16x32_bf16 v[44:47], v[132:135], v[172:175], v[44:47]
	v_mfma_f32_16x16x32_bf16 v[40:43], v[140:143], v[172:175], v[40:43]
	v_mfma_f32_16x16x32_bf16 v[28:31], v[132:135], v[196:199], v[28:31]
	v_mfma_f32_16x16x32_bf16 v[24:27], v[140:143], v[196:199], v[24:27]
	v_mfma_f32_16x16x32_bf16 v[12:15], v[132:135], v[204:207], v[12:15]
	v_mfma_f32_16x16x32_bf16 v[8:11], v[140:143], v[204:207], v[8:11]
	s_setprio 0
	s_setprio 1
	v_mfma_f32_16x16x32_bf16 v[52:55], v[144:147], v[160:163], v[52:55]
	v_mfma_f32_16x16x32_bf16 v[48:51], v[152:155], v[160:163], v[48:51]
	v_mfma_f32_16x16x32_bf16 v[36:39], v[144:147], v[168:171], v[36:39]
	v_mfma_f32_16x16x32_bf16 v[32:35], v[152:155], v[168:171], v[32:35]
	v_mfma_f32_16x16x32_bf16 v[20:23], v[144:147], v[192:195], v[20:23]
	v_mfma_f32_16x16x32_bf16 v[16:19], v[152:155], v[192:195], v[16:19]
	v_mfma_f32_16x16x32_bf16 v[4:7], v[144:147], v[200:203], v[4:7]
	v_mfma_f32_16x16x32_bf16 v[0:3], v[152:155], v[200:203], v[0:3]
	v_mfma_f32_16x16x32_bf16 v[52:55], v[148:151], v[164:167], v[52:55]
	v_mfma_f32_16x16x32_bf16 v[48:51], v[156:159], v[164:167], v[48:51]
	v_mfma_f32_16x16x32_bf16 v[36:39], v[148:151], v[172:175], v[36:39]
	v_mfma_f32_16x16x32_bf16 v[32:35], v[156:159], v[172:175], v[32:35]
	v_mfma_f32_16x16x32_bf16 v[20:23], v[148:151], v[196:199], v[20:23]
	v_mfma_f32_16x16x32_bf16 v[16:19], v[156:159], v[196:199], v[16:19]
	v_mfma_f32_16x16x32_bf16 v[4:7], v[148:151], v[204:207], v[4:7]
	v_mfma_f32_16x16x32_bf16 v[0:3], v[156:159], v[204:207], v[0:3]
	s_setprio 0
	s_barrier
	s_add_i32 s58, s58, 2
	s_add_u32 s42, s42, 0x100
	s_addc_u32 s43, s43, 0
	s_add_u32 s25, s25, 0x100
	s_addc_u32 s35, s35, 0
	s_cmp_gt_u32 s58, 29

.LBB0_635:
	s_ashr_i32 s67, s66, 31
	s_lshl_b64 s[12:13], s[66:67], 20
	s_add_u32 s70, s55, s12
	s_addc_u32 s71, s57, s13
	s_and_b64 s[6:7], s[6:7], exec
	s_cselect_b32 s1, s71, s11
	s_cselect_b32 s3, s70, s10
	s_add_u32 s6, s8, 0x80080
	s_addc_u32 s7, s9, 0
	s_add_u32 s12, s10, 0x100
	s_addc_u32 s13, s11, 0
	s_mov_b32 s15, -2
	s_waitcnt vmcnt(0)
	ds_read_b128 v[148:151], v197
	ds_read_b128 v[170:173], v197 offset:1024
	ds_read_b128 v[174:177], v197 offset:2048
	ds_read_b128 v[178:181], v197 offset:3072
	ds_read_b128 v[182:185], v198
	ds_read_b128 v[186:189], v198 offset:1024
	ds_read_b128 v[202:205], v198 offset:2048
	ds_read_b128 v[206:209], v198 offset:3072
	s_add_u32 s8, s6, 0xfff80080
	s_addc_u32 s9, s7, -1
	s_cmp_eq_u32 s15, 28
	s_cselect_b32 s11, s69, s9
	s_cselect_b32 s10, s68, s8
	s_cselect_b32 s9, s1, s13
	s_cselect_b32 s8, s3, s12
	v_lshl_add_u64 v[134:135], s[6:7], 0, v[162:163]
	s_add_i32 m0, s72, 0xc000
	ds_read_b128 v[214:217], v199
	ds_read_b128 v[218:221], v199 offset:1024
	ds_read_b128 v[222:225], v199 offset:2048
	ds_read_b128 v[226:229], v199 offset:3072
	ds_read_b128 v[230:233], v199 offset:4096
	ds_read_b128 v[234:237], v199 offset:5120
	ds_read_b128 v[238:241], v199 offset:6144
	ds_read_b128 v[242:245], v199 offset:7168
	global_load_lds_dwordx4 v[134:135], off
	v_lshl_add_u64 v[134:135], s[6:7], 0, v[164:165]
	s_add_i32 m0, s72, 0xe000
	s_nop 0
	global_load_lds_dwordx4 v[134:135], off
	s_waitcnt vmcnt(8)
	s_waitcnt lgkmcnt(0)
	s_barrier
	s_setprio 1
	s_waitcnt lgkmcnt(0)
	v_mfma_f32_16x16x32_bf16 v[112:115], v[148:151], v[214:217], 0
	v_mfma_f32_16x16x32_bf16 v[80:83], v[174:177], v[214:217], 0
	v_mfma_f32_16x16x32_bf16 v[116:119], v[148:151], v[222:225], 0
	v_mfma_f32_16x16x32_bf16 v[88:91], v[174:177], v[222:225], 0
	v_mfma_f32_16x16x32_bf16 v[124:127], v[148:151], v[230:233], 0
	v_mfma_f32_16x16x32_bf16 v[92:95], v[174:177], v[230:233], 0
	v_mfma_f32_16x16x32_bf16 v[120:123], v[148:151], v[238:241], 0
	v_mfma_f32_16x16x32_bf16 v[84:87], v[174:177], v[238:241], 0
	v_mfma_f32_16x16x32_bf16 v[112:115], v[170:173], v[218:221], v[112:115]
	v_mfma_f32_16x16x32_bf16 v[80:83], v[178:181], v[218:221], v[80:83]
	v_mfma_f32_16x16x32_bf16 v[116:119], v[170:173], v[226:229], v[116:119]
	v_mfma_f32_16x16x32_bf16 v[88:91], v[178:181], v[226:229], v[88:91]
	v_mfma_f32_16x16x32_bf16 v[124:127], v[170:173], v[234:237], v[124:127]
	v_mfma_f32_16x16x32_bf16 v[92:95], v[178:181], v[234:237], v[92:95]
	v_mfma_f32_16x16x32_bf16 v[120:123], v[170:173], v[242:245], v[120:123]
	v_mfma_f32_16x16x32_bf16 v[84:87], v[178:181], v[242:245], v[84:87]
	s_setprio 0
	s_setprio 1
	v_mfma_f32_16x16x32_bf16 v[108:111], v[182:185], v[214:217], 0
	v_mfma_f32_16x16x32_bf16 v[76:79], v[202:205], v[214:217], 0
	v_mfma_f32_16x16x32_bf16 v[104:107], v[182:185], v[222:225], 0
	v_mfma_f32_16x16x32_bf16 v[72:75], v[202:205], v[222:225], 0
	v_mfma_f32_16x16x32_bf16 v[100:103], v[182:185], v[230:233], 0
	v_mfma_f32_16x16x32_bf16 v[68:71], v[202:205], v[230:233], 0
	v_mfma_f32_16x16x32_bf16 v[96:99], v[182:185], v[238:241], 0
	v_mfma_f32_16x16x32_bf16 v[64:67], v[202:205], v[238:241], 0
	v_mfma_f32_16x16x32_bf16 v[108:111], v[186:189], v[218:221], v[108:111]
	v_mfma_f32_16x16x32_bf16 v[76:79], v[206:209], v[218:221], v[76:79]
	v_mfma_f32_16x16x32_bf16 v[104:107], v[186:189], v[226:229], v[104:107]
	v_mfma_f32_16x16x32_bf16 v[72:75], v[206:209], v[226:229], v[72:75]
	v_mfma_f32_16x16x32_bf16 v[100:103], v[186:189], v[234:237], v[100:103]
	v_mfma_f32_16x16x32_bf16 v[68:71], v[206:209], v[234:237], v[68:71]
	v_mfma_f32_16x16x32_bf16 v[96:99], v[186:189], v[242:245], v[96:99]
	v_mfma_f32_16x16x32_bf16 v[64:67], v[206:209], v[242:245], v[64:67]
	s_setprio 0
	s_barrier
	s_add_i32 s16, s94, s63
	v_lshl_add_u64 v[134:135], s[8:9], 0, v[154:155]
	s_mov_b32 m0, s16
	ds_read_b128 v[214:217], v199 offset:16384
	ds_read_b128 v[218:221], v199 offset:17408
	ds_read_b128 v[222:225], v199 offset:18432
	ds_read_b128 v[226:229], v199 offset:19456
	ds_read_b128 v[230:233], v199 offset:20480
	ds_read_b128 v[234:237], v199 offset:21504
	ds_read_b128 v[238:241], v199 offset:22528
	ds_read_b128 v[242:245], v199 offset:23552
	global_load_lds_dwordx4 v[134:135], off
	s_add_i32 m0, s16, 0x2000
	s_add_u32 s16, s8, 0x80000
	v_lshl_add_u64 v[190:191], s[8:9], 0, v[158:159]
	s_addc_u32 s17, s9, 0
	s_add_i32 s18, s95, s63
	global_load_lds_dwordx4 v[190:191], off
	v_lshl_add_u64 v[210:211], s[16:17], 0, v[154:155]
	s_mov_b32 m0, s18
	v_lshl_add_u64 v[246:247], s[10:11], 0, v[156:157]
	global_load_lds_dwordx4 v[210:211], off
	v_lshl_add_u64 v[210:211], s[16:17], 0, v[158:159]
	s_add_i32 m0, s18, 0x2000
	s_nop 0
	global_load_lds_dwordx4 v[210:211], off
	v_lshl_add_u64 v[210:211], s[10:11], 0, v[152:153]
	s_mov_b32 m0, s72
	s_nop 0
	global_load_lds_dwordx4 v[210:211], off
	s_mov_b32 m0, s73
	s_nop 0
	global_load_lds_dwordx4 v[246:247], off
	s_waitcnt vmcnt(8)
	s_waitcnt lgkmcnt(0)
	s_barrier
	s_setprio 1
	s_waitcnt lgkmcnt(0)
	v_mfma_f32_16x16x32_bf16 v[48:51], v[148:151], v[214:217], 0
	v_mfma_f32_16x16x32_bf16 v[16:19], v[174:177], v[214:217], 0
	v_mfma_f32_16x16x32_bf16 v[52:55], v[148:151], v[222:225], 0
	v_mfma_f32_16x16x32_bf16 v[24:27], v[174:177], v[222:225], 0
	v_mfma_f32_16x16x32_bf16 v[60:63], v[148:151], v[230:233], 0
	v_mfma_f32_16x16x32_bf16 v[28:31], v[174:177], v[230:233], 0
	v_mfma_f32_16x16x32_bf16 v[56:59], v[148:151], v[238:241], 0
	v_mfma_f32_16x16x32_bf16 v[20:23], v[174:177], v[238:241], 0
	v_mfma_f32_16x16x32_bf16 v[48:51], v[170:173], v[218:221], v[48:51]
	v_mfma_f32_16x16x32_bf16 v[16:19], v[178:181], v[218:221], v[16:19]
	v_mfma_f32_16x16x32_bf16 v[52:55], v[170:173], v[226:229], v[52:55]
	v_mfma_f32_16x16x32_bf16 v[24:27], v[178:181], v[226:229], v[24:27]
	v_mfma_f32_16x16x32_bf16 v[60:63], v[170:173], v[234:237], v[60:63]
	v_mfma_f32_16x16x32_bf16 v[28:31], v[178:181], v[234:237], v[28:31]
	v_mfma_f32_16x16x32_bf16 v[56:59], v[170:173], v[242:245], v[56:59]
	v_mfma_f32_16x16x32_bf16 v[20:23], v[178:181], v[242:245], v[20:23]
	s_setprio 0
	s_setprio 1
	v_mfma_f32_16x16x32_bf16 v[44:47], v[182:185], v[214:217], 0
	v_mfma_f32_16x16x32_bf16 v[12:15], v[202:205], v[214:217], 0
	v_mfma_f32_16x16x32_bf16 v[40:43], v[182:185], v[222:225], 0
	v_mfma_f32_16x16x32_bf16 v[8:11], v[202:205], v[222:225], 0
	v_mfma_f32_16x16x32_bf16 v[36:39], v[182:185], v[230:233], 0
	v_mfma_f32_16x16x32_bf16 v[4:7], v[202:205], v[230:233], 0
	v_mfma_f32_16x16x32_bf16 v[32:35], v[182:185], v[238:241], 0
	v_mfma_f32_16x16x32_bf16 v[0:3], v[202:205], v[238:241], 0
	v_mfma_f32_16x16x32_bf16 v[44:47], v[186:189], v[218:221], v[44:47]
	v_mfma_f32_16x16x32_bf16 v[12:15], v[206:209], v[218:221], v[12:15]
	v_mfma_f32_16x16x32_bf16 v[40:43], v[186:189], v[226:229], v[40:43]
	v_mfma_f32_16x16x32_bf16 v[8:11], v[206:209], v[226:229], v[8:11]
	v_mfma_f32_16x16x32_bf16 v[36:39], v[186:189], v[234:237], v[36:39]
	v_mfma_f32_16x16x32_bf16 v[4:7], v[206:209], v[234:237], v[4:7]
	v_mfma_f32_16x16x32_bf16 v[32:35], v[186:189], v[242:245], v[32:35]
	v_mfma_f32_16x16x32_bf16 v[0:3], v[206:209], v[242:245], v[0:3]
	s_setprio 0
	s_barrier
	s_add_i32 s16, 0, 0x18000
	s_add_i32 s17, 0, 0x1c000
	v_add_u32_e32 v178, s16, v196
	v_add_u32_e32 v201, s17, v196
	ds_read_b128 v[148:151], v178
	ds_read_b128 v[170:173], v178 offset:1024
	ds_read_b128 v[174:177], v178 offset:2048
	ds_read_b128 v[178:181], v178 offset:3072
	ds_read_b128 v[182:185], v201
	ds_read_b128 v[186:189], v201 offset:1024
	ds_read_b128 v[202:205], v201 offset:2048
	ds_read_b128 v[206:209], v201 offset:3072
	s_add_u32 s10, s10, 0x80000
	s_addc_u32 s11, s11, 0
	s_mov_b32 m0, s74
	v_lshl_add_u64 v[248:249], s[10:11], 0, v[152:153]
	ds_read_b128 v[214:217], v199 offset:32768
	ds_read_b128 v[218:221], v199 offset:33792
	ds_read_b128 v[222:225], v199 offset:34816
	ds_read_b128 v[226:229], v199 offset:35840
	ds_read_b128 v[230:233], v199 offset:36864
	ds_read_b128 v[234:237], v199 offset:37888
	ds_read_b128 v[238:241], v199 offset:38912
	ds_read_b128 v[242:245], v199 offset:39936
	global_load_lds_dwordx4 v[248:249], off
	v_lshl_add_u64 v[248:249], s[10:11], 0, v[156:157]
	s_mov_b32 m0, s75
	s_nop 0
	global_load_lds_dwordx4 v[248:249], off
	s_waitcnt vmcnt(8)
	s_waitcnt lgkmcnt(0)
	s_barrier
	s_setprio 1
	s_waitcnt lgkmcnt(0)
	v_mfma_f32_16x16x32_bf16 v[112:115], v[148:151], v[214:217], v[112:115]
	v_mfma_f32_16x16x32_bf16 v[80:83], v[174:177], v[214:217], v[80:83]
	v_mfma_f32_16x16x32_bf16 v[116:119], v[148:151], v[222:225], v[116:119]
	v_mfma_f32_16x16x32_bf16 v[88:91], v[174:177], v[222:225], v[88:91]
	v_mfma_f32_16x16x32_bf16 v[124:127], v[148:151], v[230:233], v[124:127]
	v_mfma_f32_16x16x32_bf16 v[92:95], v[174:177], v[230:233], v[92:95]
	v_mfma_f32_16x16x32_bf16 v[120:123], v[148:151], v[238:241], v[120:123]
	v_mfma_f32_16x16x32_bf16 v[84:87], v[174:177], v[238:241], v[84:87]
	v_mfma_f32_16x16x32_bf16 v[112:115], v[170:173], v[218:221], v[112:115]
	v_mfma_f32_16x16x32_bf16 v[80:83], v[178:181], v[218:221], v[80:83]
	v_mfma_f32_16x16x32_bf16 v[116:119], v[170:173], v[226:229], v[116:119]
	v_mfma_f32_16x16x32_bf16 v[88:91], v[178:181], v[226:229], v[88:91]
	v_mfma_f32_16x16x32_bf16 v[124:127], v[170:173], v[234:237], v[124:127]
	v_mfma_f32_16x16x32_bf16 v[92:95], v[178:181], v[234:237], v[92:95]
	v_mfma_f32_16x16x32_bf16 v[120:123], v[170:173], v[242:245], v[120:123]
	v_mfma_f32_16x16x32_bf16 v[84:87], v[178:181], v[242:245], v[84:87]
	s_setprio 0
	s_setprio 1
	v_mfma_f32_16x16x32_bf16 v[108:111], v[182:185], v[214:217], v[108:111]
	v_mfma_f32_16x16x32_bf16 v[76:79], v[202:205], v[214:217], v[76:79]
	v_mfma_f32_16x16x32_bf16 v[104:107], v[182:185], v[222:225], v[104:107]
	v_mfma_f32_16x16x32_bf16 v[72:75], v[202:205], v[222:225], v[72:75]
	v_mfma_f32_16x16x32_bf16 v[100:103], v[182:185], v[230:233], v[100:103]
	v_mfma_f32_16x16x32_bf16 v[68:71], v[202:205], v[230:233], v[68:71]
	v_mfma_f32_16x16x32_bf16 v[96:99], v[182:185], v[238:241], v[96:99]
	v_mfma_f32_16x16x32_bf16 v[64:67], v[202:205], v[238:241], v[64:67]
	v_mfma_f32_16x16x32_bf16 v[108:111], v[186:189], v[218:221], v[108:111]
	v_mfma_f32_16x16x32_bf16 v[76:79], v[206:209], v[218:221], v[76:79]
	v_mfma_f32_16x16x32_bf16 v[104:107], v[186:189], v[226:229], v[104:107]
	v_mfma_f32_16x16x32_bf16 v[72:75], v[206:209], v[226:229], v[72:75]
	v_mfma_f32_16x16x32_bf16 v[100:103], v[186:189], v[234:237], v[100:103]
	v_mfma_f32_16x16x32_bf16 v[68:71], v[206:209], v[234:237], v[68:71]
	v_mfma_f32_16x16x32_bf16 v[96:99], v[186:189], v[242:245], v[96:99]
	v_mfma_f32_16x16x32_bf16 v[64:67], v[206:209], v[242:245], v[64:67]
	s_setprio 0
	s_barrier
	s_add_i32 s10, s16, s63
	v_lshl_add_u64 v[134:135], v[134:135], 0, s[40:41]
	s_mov_b32 m0, s10
	ds_read_b128 v[214:217], v199 offset:49152
	ds_read_b128 v[218:221], v199 offset:50176
	ds_read_b128 v[222:225], v199 offset:51200
	ds_read_b128 v[226:229], v199 offset:52224
	ds_read_b128 v[230:233], v199 offset:53248
	ds_read_b128 v[234:237], v199 offset:54272
	ds_read_b128 v[238:241], v199 offset:55296
	ds_read_b128 v[242:245], v199 offset:56320
	global_load_lds_dwordx4 v[134:135], off
	s_add_i32 m0, s10, 0x2000
	s_add_u32 s8, s8, 0x80080
	v_lshl_add_u64 v[134:135], v[190:191], 0, s[40:41]
	s_addc_u32 s9, s9, 0
	s_add_i32 s10, s17, s63
	global_load_lds_dwordx4 v[134:135], off
	v_lshl_add_u64 v[134:135], s[8:9], 0, v[154:155]
	s_mov_b32 m0, s10
	s_nop 0
	global_load_lds_dwordx4 v[134:135], off
	v_lshl_add_u64 v[134:135], s[8:9], 0, v[158:159]
	s_add_i32 m0, s10, 0x2000
	s_nop 0
	global_load_lds_dwordx4 v[134:135], off
	v_lshl_add_u64 v[134:135], v[210:211], 0, s[40:41]
	s_mov_b32 m0, s82
	s_nop 0
	global_load_lds_dwordx4 v[134:135], off
	v_lshl_add_u64 v[134:135], v[246:247], 0, s[40:41]
	s_mov_b32 m0, s83
	s_nop 0
	global_load_lds_dwordx4 v[134:135], off
	s_waitcnt vmcnt(8)
	s_waitcnt lgkmcnt(0)
	s_barrier
	s_setprio 1
	s_waitcnt lgkmcnt(0)
	v_mfma_f32_16x16x32_bf16 v[48:51], v[148:151], v[214:217], v[48:51]
	v_mfma_f32_16x16x32_bf16 v[16:19], v[174:177], v[214:217], v[16:19]
	v_mfma_f32_16x16x32_bf16 v[52:55], v[148:151], v[222:225], v[52:55]
	v_mfma_f32_16x16x32_bf16 v[24:27], v[174:177], v[222:225], v[24:27]
	v_mfma_f32_16x16x32_bf16 v[60:63], v[148:151], v[230:233], v[60:63]
	v_mfma_f32_16x16x32_bf16 v[28:31], v[174:177], v[230:233], v[28:31]
	v_mfma_f32_16x16x32_bf16 v[56:59], v[148:151], v[238:241], v[56:59]
	v_mfma_f32_16x16x32_bf16 v[20:23], v[174:177], v[238:241], v[20:23]
	v_mfma_f32_16x16x32_bf16 v[48:51], v[170:173], v[218:221], v[48:51]
	v_mfma_f32_16x16x32_bf16 v[16:19], v[178:181], v[218:221], v[16:19]
	v_mfma_f32_16x16x32_bf16 v[52:55], v[170:173], v[226:229], v[52:55]
	v_mfma_f32_16x16x32_bf16 v[24:27], v[178:181], v[226:229], v[24:27]
	v_mfma_f32_16x16x32_bf16 v[60:63], v[170:173], v[234:237], v[60:63]
	v_mfma_f32_16x16x32_bf16 v[28:31], v[178:181], v[234:237], v[28:31]
	v_mfma_f32_16x16x32_bf16 v[56:59], v[170:173], v[242:245], v[56:59]
	v_mfma_f32_16x16x32_bf16 v[20:23], v[178:181], v[242:245], v[20:23]
	s_setprio 0
	s_setprio 1
	v_mfma_f32_16x16x32_bf16 v[44:47], v[182:185], v[214:217], v[44:47]
	v_mfma_f32_16x16x32_bf16 v[12:15], v[202:205], v[214:217], v[12:15]
	v_mfma_f32_16x16x32_bf16 v[40:43], v[182:185], v[222:225], v[40:43]
	v_mfma_f32_16x16x32_bf16 v[8:11], v[202:205], v[222:225], v[8:11]
	v_mfma_f32_16x16x32_bf16 v[36:39], v[182:185], v[230:233], v[36:39]
	v_mfma_f32_16x16x32_bf16 v[4:7], v[202:205], v[230:233], v[4:7]
	v_mfma_f32_16x16x32_bf16 v[32:35], v[182:185], v[238:241], v[32:35]
	v_mfma_f32_16x16x32_bf16 v[0:3], v[202:205], v[238:241], v[0:3]
	v_mfma_f32_16x16x32_bf16 v[44:47], v[186:189], v[218:221], v[44:47]
	v_mfma_f32_16x16x32_bf16 v[12:15], v[206:209], v[218:221], v[12:15]
	v_mfma_f32_16x16x32_bf16 v[40:43], v[186:189], v[226:229], v[40:43]
	v_mfma_f32_16x16x32_bf16 v[8:11], v[206:209], v[226:229], v[8:11]
	v_mfma_f32_16x16x32_bf16 v[36:39], v[186:189], v[234:237], v[36:39]
	v_mfma_f32_16x16x32_bf16 v[4:7], v[206:209], v[234:237], v[4:7]
	v_mfma_f32_16x16x32_bf16 v[32:35], v[186:189], v[242:245], v[32:35]
	v_mfma_f32_16x16x32_bf16 v[0:3], v[206:209], v[242:245], v[0:3]
	s_setprio 0
	s_barrier
	s_add_i32 s15, s15, 2
	s_add_u32 s6, s6, 0x100
	s_addc_u32 s7, s7, 0
	s_add_u32 s12, s12, 0x100
	s_addc_u32 s13, s13, 0
	s_cmp_gt_u32 s15, 29

.LBB0_875:
	s_mov_b32 s1, -2
	s_mov_b64 s[4:5], s[22:23]
	ds_read_b128 v[128:131], v188
	ds_read_b128 v[132:135], v188 offset:1024
	ds_read_b128 v[136:139], v188 offset:2048
	ds_read_b128 v[140:143], v188 offset:3072
	ds_read_b128 v[144:147], v189
	ds_read_b128 v[148:151], v189 offset:1024
	ds_read_b128 v[166:169], v189 offset:2048
	ds_read_b128 v[170:173], v189 offset:3072
	s_add_u32 s40, s38, 0x100
	s_addc_u32 s41, s39, 0
	s_cmpk_eq_i32 s1, 0x52
	s_cselect_b32 s45, s37, s41
	s_cselect_b32 s44, s36, s40
	s_cselect_b32 s43, s17, s5
	s_cselect_b32 s42, s16, s4
	v_lshl_add_u64 v[182:183], s[38:39], 0, v[160:161]
	s_add_i32 m0, s48, 0xc000
	ds_read_b128 v[174:177], v190
	ds_read_b128 v[178:181], v190 offset:1024
	ds_read_b128 v[194:197], v190 offset:2048
	ds_read_b128 v[198:201], v190 offset:3072
	ds_read_b128 v[202:205], v190 offset:4096
	ds_read_b128 v[206:209], v190 offset:5120
	ds_read_b128 v[210:213], v190 offset:6144
	ds_read_b128 v[214:217], v190 offset:7168
	global_load_lds_dwordx4 v[182:183], off
	v_lshl_add_u64 v[182:183], s[38:39], 0, v[162:163]
	s_add_i32 m0, s48, 0xe000
	s_nop 0
	global_load_lds_dwordx4 v[182:183], off
	s_waitcnt vmcnt(8)
	s_waitcnt lgkmcnt(0)
	s_barrier
	s_setprio 1
	s_waitcnt lgkmcnt(0)
	v_mfma_f32_16x16x32_bf16 v[124:127], v[128:131], v[174:177], 0
	v_mfma_f32_16x16x32_bf16 v[120:123], v[136:139], v[174:177], 0
	v_mfma_f32_16x16x32_bf16 v[108:111], v[128:131], v[194:197], 0
	v_mfma_f32_16x16x32_bf16 v[104:107], v[136:139], v[194:197], 0
	v_mfma_f32_16x16x32_bf16 v[92:95], v[128:131], v[202:205], 0
	v_mfma_f32_16x16x32_bf16 v[88:91], v[136:139], v[202:205], 0
	v_mfma_f32_16x16x32_bf16 v[76:79], v[128:131], v[210:213], 0
	v_mfma_f32_16x16x32_bf16 v[72:75], v[136:139], v[210:213], 0
	v_mfma_f32_16x16x32_bf16 v[124:127], v[132:135], v[178:181], v[124:127]
	v_mfma_f32_16x16x32_bf16 v[120:123], v[140:143], v[178:181], v[120:123]
	v_mfma_f32_16x16x32_bf16 v[108:111], v[132:135], v[198:201], v[108:111]
	v_mfma_f32_16x16x32_bf16 v[104:107], v[140:143], v[198:201], v[104:107]
	v_mfma_f32_16x16x32_bf16 v[92:95], v[132:135], v[206:209], v[92:95]
	v_mfma_f32_16x16x32_bf16 v[88:91], v[140:143], v[206:209], v[88:91]
	v_mfma_f32_16x16x32_bf16 v[76:79], v[132:135], v[214:217], v[76:79]
	v_mfma_f32_16x16x32_bf16 v[72:75], v[140:143], v[214:217], v[72:75]
	s_setprio 0
	s_setprio 1
	v_mfma_f32_16x16x32_bf16 v[116:119], v[144:147], v[174:177], 0
	v_mfma_f32_16x16x32_bf16 v[112:115], v[166:169], v[174:177], 0
	v_mfma_f32_16x16x32_bf16 v[100:103], v[144:147], v[194:197], 0
	v_mfma_f32_16x16x32_bf16 v[96:99], v[166:169], v[194:197], 0
	v_mfma_f32_16x16x32_bf16 v[84:87], v[144:147], v[202:205], 0
	v_mfma_f32_16x16x32_bf16 v[80:83], v[166:169], v[202:205], 0
	v_mfma_f32_16x16x32_bf16 v[68:71], v[144:147], v[210:213], 0
	v_mfma_f32_16x16x32_bf16 v[64:67], v[166:169], v[210:213], 0
	v_mfma_f32_16x16x32_bf16 v[116:119], v[148:151], v[178:181], v[116:119]
	v_mfma_f32_16x16x32_bf16 v[112:115], v[170:173], v[178:181], v[112:115]
	v_mfma_f32_16x16x32_bf16 v[100:103], v[148:151], v[198:201], v[100:103]
	v_mfma_f32_16x16x32_bf16 v[96:99], v[170:173], v[198:201], v[96:99]
	v_mfma_f32_16x16x32_bf16 v[84:87], v[148:151], v[206:209], v[84:87]
	v_mfma_f32_16x16x32_bf16 v[80:83], v[170:173], v[206:209], v[80:83]
	v_mfma_f32_16x16x32_bf16 v[68:71], v[148:151], v[214:217], v[68:71]
	v_mfma_f32_16x16x32_bf16 v[64:67], v[170:173], v[214:217], v[64:67]
	s_setprio 0
	s_barrier
	s_add_i32 s3, s70, s33
	v_lshl_add_u64 v[182:183], s[42:43], 0, v[154:155]
	s_mov_b32 m0, s3
	ds_read_b128 v[174:177], v190 offset:16384
	ds_read_b128 v[178:181], v190 offset:17408
	ds_read_b128 v[194:197], v190 offset:18432
	ds_read_b128 v[198:201], v190 offset:19456
	ds_read_b128 v[202:205], v190 offset:20480
	ds_read_b128 v[206:209], v190 offset:21504
	ds_read_b128 v[210:213], v190 offset:22528
	ds_read_b128 v[214:217], v190 offset:23552
	global_load_lds_dwordx4 v[182:183], off
	s_add_i32 m0, s3, 0x2000
	s_add_u32 s38, s42, 0x158000
	v_lshl_add_u64 v[218:219], s[42:43], 0, v[158:159]
	s_addc_u32 s39, s43, 0
	s_add_i32 s3, s71, s33
	global_load_lds_dwordx4 v[218:219], off
	v_lshl_add_u64 v[220:221], s[38:39], 0, v[154:155]
	s_mov_b32 m0, s3
	v_lshl_add_u64 v[222:223], s[44:45], 0, v[156:157]
	global_load_lds_dwordx4 v[220:221], off
	v_lshl_add_u64 v[220:221], s[38:39], 0, v[158:159]
	s_add_i32 m0, s3, 0x2000
	s_nop 0
	global_load_lds_dwordx4 v[220:221], off
	v_lshl_add_u64 v[220:221], s[44:45], 0, v[152:153]
	s_mov_b32 m0, s48
	s_nop 0
	global_load_lds_dwordx4 v[220:221], off
	s_mov_b32 m0, s49
	s_nop 0
	global_load_lds_dwordx4 v[222:223], off
	s_waitcnt vmcnt(8)
	s_waitcnt lgkmcnt(0)
	s_barrier
	s_setprio 1
	s_waitcnt lgkmcnt(0)
	v_mfma_f32_16x16x32_bf16 v[60:63], v[128:131], v[174:177], 0
	v_mfma_f32_16x16x32_bf16 v[56:59], v[136:139], v[174:177], 0
	v_mfma_f32_16x16x32_bf16 v[44:47], v[128:131], v[194:197], 0
	v_mfma_f32_16x16x32_bf16 v[40:43], v[136:139], v[194:197], 0
	v_mfma_f32_16x16x32_bf16 v[28:31], v[128:131], v[202:205], 0
	v_mfma_f32_16x16x32_bf16 v[24:27], v[136:139], v[202:205], 0
	v_mfma_f32_16x16x32_bf16 v[12:15], v[128:131], v[210:213], 0
	v_mfma_f32_16x16x32_bf16 v[8:11], v[136:139], v[210:213], 0
	v_mfma_f32_16x16x32_bf16 v[60:63], v[132:135], v[178:181], v[60:63]
	v_mfma_f32_16x16x32_bf16 v[56:59], v[140:143], v[178:181], v[56:59]
	v_mfma_f32_16x16x32_bf16 v[44:47], v[132:135], v[198:201], v[44:47]
	v_mfma_f32_16x16x32_bf16 v[40:43], v[140:143], v[198:201], v[40:43]
	v_mfma_f32_16x16x32_bf16 v[28:31], v[132:135], v[206:209], v[28:31]
	v_mfma_f32_16x16x32_bf16 v[24:27], v[140:143], v[206:209], v[24:27]
	v_mfma_f32_16x16x32_bf16 v[12:15], v[132:135], v[214:217], v[12:15]
	v_mfma_f32_16x16x32_bf16 v[8:11], v[140:143], v[214:217], v[8:11]
	s_setprio 0
	s_setprio 1
	v_mfma_f32_16x16x32_bf16 v[52:55], v[144:147], v[174:177], 0
	v_mfma_f32_16x16x32_bf16 v[48:51], v[166:169], v[174:177], 0
	v_mfma_f32_16x16x32_bf16 v[36:39], v[144:147], v[194:197], 0
	v_mfma_f32_16x16x32_bf16 v[32:35], v[166:169], v[194:197], 0
	v_mfma_f32_16x16x32_bf16 v[20:23], v[144:147], v[202:205], 0
	v_mfma_f32_16x16x32_bf16 v[16:19], v[166:169], v[202:205], 0
	v_mfma_f32_16x16x32_bf16 v[4:7], v[144:147], v[210:213], 0
	v_mfma_f32_16x16x32_bf16 v[0:3], v[166:169], v[210:213], 0
	v_mfma_f32_16x16x32_bf16 v[52:55], v[148:151], v[178:181], v[52:55]
	v_mfma_f32_16x16x32_bf16 v[48:51], v[170:173], v[178:181], v[48:51]
	v_mfma_f32_16x16x32_bf16 v[36:39], v[148:151], v[198:201], v[36:39]
	v_mfma_f32_16x16x32_bf16 v[32:35], v[170:173], v[198:201], v[32:35]
	v_mfma_f32_16x16x32_bf16 v[20:23], v[148:151], v[206:209], v[20:23]
	v_mfma_f32_16x16x32_bf16 v[16:19], v[170:173], v[206:209], v[16:19]
	v_mfma_f32_16x16x32_bf16 v[4:7], v[148:151], v[214:217], v[4:7]
	v_mfma_f32_16x16x32_bf16 v[0:3], v[170:173], v[214:217], v[0:3]
	s_setprio 0
	s_barrier
	s_add_i32 s3, 0, 0x18000
	s_add_i32 s73, 0, 0x1c000
	v_add_u32_e32 v140, s3, v187
	v_add_u32_e32 v170, s73, v187
	ds_read_b128 v[128:131], v140
	ds_read_b128 v[132:135], v140 offset:1024
	ds_read_b128 v[136:139], v140 offset:2048
	ds_read_b128 v[140:143], v140 offset:3072
	ds_read_b128 v[144:147], v170
	ds_read_b128 v[148:151], v170 offset:1024
	ds_read_b128 v[166:169], v170 offset:2048
	ds_read_b128 v[170:173], v170 offset:3072
	s_add_u32 s38, s44, 0x158000
	s_addc_u32 s39, s45, 0
	s_mov_b32 m0, s51
	v_lshl_add_u64 v[224:225], s[38:39], 0, v[152:153]
	ds_read_b128 v[174:177], v190 offset:32768
	ds_read_b128 v[178:181], v190 offset:33792
	ds_read_b128 v[194:197], v190 offset:34816
	ds_read_b128 v[198:201], v190 offset:35840
	ds_read_b128 v[202:205], v190 offset:36864
	ds_read_b128 v[206:209], v190 offset:37888
	ds_read_b128 v[210:213], v190 offset:38912
	ds_read_b128 v[214:217], v190 offset:39936
	global_load_lds_dwordx4 v[224:225], off
	v_lshl_add_u64 v[224:225], s[38:39], 0, v[156:157]
	s_mov_b32 m0, s52
	s_nop 0
	global_load_lds_dwordx4 v[224:225], off
	s_waitcnt vmcnt(8)
	s_waitcnt lgkmcnt(0)
	s_barrier
	s_setprio 1
	s_waitcnt lgkmcnt(0)
	v_mfma_f32_16x16x32_bf16 v[124:127], v[128:131], v[174:177], v[124:127]
	v_mfma_f32_16x16x32_bf16 v[120:123], v[136:139], v[174:177], v[120:123]
	v_mfma_f32_16x16x32_bf16 v[108:111], v[128:131], v[194:197], v[108:111]
	v_mfma_f32_16x16x32_bf16 v[104:107], v[136:139], v[194:197], v[104:107]
	v_mfma_f32_16x16x32_bf16 v[92:95], v[128:131], v[202:205], v[92:95]
	v_mfma_f32_16x16x32_bf16 v[88:91], v[136:139], v[202:205], v[88:91]
	v_mfma_f32_16x16x32_bf16 v[76:79], v[128:131], v[210:213], v[76:79]
	v_mfma_f32_16x16x32_bf16 v[72:75], v[136:139], v[210:213], v[72:75]
	v_mfma_f32_16x16x32_bf16 v[124:127], v[132:135], v[178:181], v[124:127]
	v_mfma_f32_16x16x32_bf16 v[120:123], v[140:143], v[178:181], v[120:123]
	v_mfma_f32_16x16x32_bf16 v[108:111], v[132:135], v[198:201], v[108:111]
	v_mfma_f32_16x16x32_bf16 v[104:107], v[140:143], v[198:201], v[104:107]
	v_mfma_f32_16x16x32_bf16 v[92:95], v[132:135], v[206:209], v[92:95]
	v_mfma_f32_16x16x32_bf16 v[88:91], v[140:143], v[206:209], v[88:91]
	v_mfma_f32_16x16x32_bf16 v[76:79], v[132:135], v[214:217], v[76:79]
	v_mfma_f32_16x16x32_bf16 v[72:75], v[140:143], v[214:217], v[72:75]
	s_setprio 0
	s_setprio 1
	v_mfma_f32_16x16x32_bf16 v[116:119], v[144:147], v[174:177], v[116:119]
	v_mfma_f32_16x16x32_bf16 v[112:115], v[166:169], v[174:177], v[112:115]
	v_mfma_f32_16x16x32_bf16 v[100:103], v[144:147], v[194:197], v[100:103]
	v_mfma_f32_16x16x32_bf16 v[96:99], v[166:169], v[194:197], v[96:99]
	v_mfma_f32_16x16x32_bf16 v[84:87], v[144:147], v[202:205], v[84:87]
	v_mfma_f32_16x16x32_bf16 v[80:83], v[166:169], v[202:205], v[80:83]
	v_mfma_f32_16x16x32_bf16 v[68:71], v[144:147], v[210:213], v[68:71]
	v_mfma_f32_16x16x32_bf16 v[64:67], v[166:169], v[210:213], v[64:67]
	v_mfma_f32_16x16x32_bf16 v[116:119], v[148:151], v[178:181], v[116:119]
	v_mfma_f32_16x16x32_bf16 v[112:115], v[170:173], v[178:181], v[112:115]
	v_mfma_f32_16x16x32_bf16 v[100:103], v[148:151], v[198:201], v[100:103]
	v_mfma_f32_16x16x32_bf16 v[96:99], v[170:173], v[198:201], v[96:99]
	v_mfma_f32_16x16x32_bf16 v[84:87], v[148:151], v[206:209], v[84:87]
	v_mfma_f32_16x16x32_bf16 v[80:83], v[170:173], v[206:209], v[80:83]
	v_mfma_f32_16x16x32_bf16 v[68:71], v[148:151], v[214:217], v[68:71]
	v_mfma_f32_16x16x32_bf16 v[64:67], v[170:173], v[214:217], v[64:67]
	s_setprio 0
	s_barrier
	s_add_i32 s3, s3, s33
	v_lshl_add_u64 v[182:183], v[182:183], 0, s[24:25]
	s_mov_b32 m0, s3
	ds_read_b128 v[174:177], v190 offset:49152
	ds_read_b128 v[178:181], v190 offset:50176
	ds_read_b128 v[194:197], v190 offset:51200
	ds_read_b128 v[198:201], v190 offset:52224
	ds_read_b128 v[202:205], v190 offset:53248
	ds_read_b128 v[206:209], v190 offset:54272
	ds_read_b128 v[210:213], v190 offset:55296
	ds_read_b128 v[214:217], v190 offset:56320
	global_load_lds_dwordx4 v[182:183], off
	s_add_i32 m0, s3, 0x2000
	s_add_u32 s38, s42, 0x158080
	v_lshl_add_u64 v[182:183], v[218:219], 0, s[24:25]
	s_addc_u32 s39, s43, 0
	s_add_i32 s3, s73, s33
	global_load_lds_dwordx4 v[182:183], off
	v_lshl_add_u64 v[182:183], s[38:39], 0, v[154:155]
	s_mov_b32 m0, s3
	s_nop 0
	global_load_lds_dwordx4 v[182:183], off
	v_lshl_add_u64 v[182:183], s[38:39], 0, v[158:159]
	s_add_i32 m0, s3, 0x2000
	s_nop 0
	global_load_lds_dwordx4 v[182:183], off
	v_lshl_add_u64 v[182:183], v[220:221], 0, s[24:25]
	s_mov_b32 m0, s56
	s_nop 0
	global_load_lds_dwordx4 v[182:183], off
	v_lshl_add_u64 v[182:183], v[222:223], 0, s[24:25]
	s_mov_b32 m0, s57
	s_nop 0
	global_load_lds_dwordx4 v[182:183], off
	s_waitcnt vmcnt(8)
	s_waitcnt lgkmcnt(0)
	s_barrier
	s_setprio 1
	s_waitcnt lgkmcnt(0)
	v_mfma_f32_16x16x32_bf16 v[60:63], v[128:131], v[174:177], v[60:63]
	v_mfma_f32_16x16x32_bf16 v[56:59], v[136:139], v[174:177], v[56:59]
	v_mfma_f32_16x16x32_bf16 v[44:47], v[128:131], v[194:197], v[44:47]
	v_mfma_f32_16x16x32_bf16 v[40:43], v[136:139], v[194:197], v[40:43]
	v_mfma_f32_16x16x32_bf16 v[28:31], v[128:131], v[202:205], v[28:31]
	v_mfma_f32_16x16x32_bf16 v[24:27], v[136:139], v[202:205], v[24:27]
	v_mfma_f32_16x16x32_bf16 v[12:15], v[128:131], v[210:213], v[12:15]
	v_mfma_f32_16x16x32_bf16 v[8:11], v[136:139], v[210:213], v[8:11]
	v_mfma_f32_16x16x32_bf16 v[60:63], v[132:135], v[178:181], v[60:63]
	v_mfma_f32_16x16x32_bf16 v[56:59], v[140:143], v[178:181], v[56:59]
	v_mfma_f32_16x16x32_bf16 v[44:47], v[132:135], v[198:201], v[44:47]
	v_mfma_f32_16x16x32_bf16 v[40:43], v[140:143], v[198:201], v[40:43]
	v_mfma_f32_16x16x32_bf16 v[28:31], v[132:135], v[206:209], v[28:31]
	v_mfma_f32_16x16x32_bf16 v[24:27], v[140:143], v[206:209], v[24:27]
	v_mfma_f32_16x16x32_bf16 v[12:15], v[132:135], v[214:217], v[12:15]
	v_mfma_f32_16x16x32_bf16 v[8:11], v[140:143], v[214:217], v[8:11]
	s_setprio 0
	s_setprio 1
	v_mfma_f32_16x16x32_bf16 v[52:55], v[144:147], v[174:177], v[52:55]
	v_mfma_f32_16x16x32_bf16 v[48:51], v[166:169], v[174:177], v[48:51]
	v_mfma_f32_16x16x32_bf16 v[36:39], v[144:147], v[194:197], v[36:39]
	v_mfma_f32_16x16x32_bf16 v[32:35], v[166:169], v[194:197], v[32:35]
	v_mfma_f32_16x16x32_bf16 v[20:23], v[144:147], v[202:205], v[20:23]
	v_mfma_f32_16x16x32_bf16 v[16:19], v[166:169], v[202:205], v[16:19]
	v_mfma_f32_16x16x32_bf16 v[4:7], v[144:147], v[210:213], v[4:7]
	v_mfma_f32_16x16x32_bf16 v[0:3], v[166:169], v[210:213], v[0:3]
	v_mfma_f32_16x16x32_bf16 v[52:55], v[148:151], v[178:181], v[52:55]
	v_mfma_f32_16x16x32_bf16 v[48:51], v[170:173], v[178:181], v[48:51]
	v_mfma_f32_16x16x32_bf16 v[36:39], v[148:151], v[198:201], v[36:39]
	v_mfma_f32_16x16x32_bf16 v[32:35], v[170:173], v[198:201], v[32:35]
	v_mfma_f32_16x16x32_bf16 v[20:23], v[148:151], v[206:209], v[20:23]
	v_mfma_f32_16x16x32_bf16 v[16:19], v[170:173], v[206:209], v[16:19]
	v_mfma_f32_16x16x32_bf16 v[4:7], v[148:151], v[214:217], v[4:7]
	v_mfma_f32_16x16x32_bf16 v[0:3], v[170:173], v[214:217], v[0:3]
	s_setprio 0
	s_barrier
	s_add_i32 s1, s1, 2
	s_add_u32 s4, s4, 0x100
	s_addc_u32 s5, s5, 0
	s_cmpk_gt_u32 s1, 0x53
	s_mov_b64 s[38:39], s[40:41]
